# q4c + residual epilogue re-scheduled: 3 residual slots, loads issued 3 groups ahead of stores, counted vmcnt waits (never wait on just-issued stores)
# speedup vs baseline: 1.0062x; 1.0062x over previous
;     __device__ __forceinline__ void operator()(const f32x4 (&acc)[2][2][4][2], const Unit& u, int wr, int wc, int fr, int fq) const {
;         const bool lat = u.pm < 64; const int r = lat ? (u.pm >> 3) : 8;
;         const float* s = lat ? src_lat : src_ctx; float* d = lat ? dst_lat : dst_ctx;
;         const int row0 = (lat ? u.pm : u.pm - 64) * BM + wr * 64 + fr, col0 = u.pn * BM + wc * 32 + 4 * fq;
;         const float* g = gate + (size_t)r * 12288 + col0;
;         f32x4 gv[2][2];
; #pragma unroll
;         for (int bj = 0; bj < 2; ++bj)
; #pragma unroll
;             for (int n = 0; n < 2; ++n) gv[bj][n] = *(const f32x4*)(g + bj * HALF + n * 16);
;         f32x4 xc[2][2], xn[2][2];
; #pragma unroll
;         for (int bj = 0; bj < 2; ++bj)
; #pragma unroll
;             for (int n = 0; n < 2; ++n) xc[bj][n] = *(const f32x4*)(s + (size_t)row0 * DM + col0 + bj * HALF + n * 16);
; #pragma unroll
;         for (int gi = 0; gi < 8; ++gi) { const int ai = gi >> 2, m = gi & 3; const size_t off = (size_t)(row0 + ai * HALF + m * 16) * DM + col0;
;             if (gi + 1 < 8) { const int ai2 = (gi + 1) >> 2, m2 = (gi + 1) & 3; const size_t off2 = (size_t)(row0 + ai2 * HALF + m2 * 16) * DM + col0;
; #pragma unroll
;                 for (int bj = 0; bj < 2; ++bj)
; #pragma unroll
;                     for (int n = 0; n < 2; ++n) xn[bj][n] = *(const f32x4*)(s + off2 + bj * HALF + n * 16); }
; #pragma unroll
;             for (int bj = 0; bj < 2; ++bj)
; #pragma unroll
;                 for (int n = 0; n < 2; ++n) *(f32x4*)(d + off + bj * HALF + n * 16) = xc[bj][n] + gv[bj][n] * acc[ai][bj][m][n];
; #pragma unroll
;             for (int bj = 0; bj < 2; ++bj)
; #pragma unroll
;                 for (int n = 0; n < 2; ++n) xc[bj][n] = xn[bj][n]; }
;     }
.LBB0_36:
	s_lshl_b32 s8, s8, 8
	s_add_i32 s25, s8, 0xffffc000
	s_and_b64 s[38:39], s[50:51], exec
	s_cselect_b32 s8, s8, s25
	v_add_u32_e32 v152, s8, v162
	v_lshl_or_b32 v66, s70, 8, v164
	s_lshl_b64 s[38:39], s[52:53], 2
	v_ashrrev_i32_e32 v153, 31, v152
	s_add_u32 s38, s64, s38
	v_ashrrev_i32_e32 v67, 31, v66
	v_lshlrev_b64 v[194:195], 13, v[152:153]
	s_addc_u32 s39, s65, s39
	v_lshlrev_b64 v[160:161], 2, v[66:67]
	v_lshl_add_u64 v[154:155], s[28:29], 0, v[194:195]
	v_lshl_add_u64 v[66:67], s[38:39], 0, v[160:161]
	v_lshl_add_u64 v[174:175], v[154:155], 0, v[160:161]
	global_load_dwordx4 v[78:81], v[66:67], off
	global_load_dwordx4 v[74:77], v[66:67], off offset:64
	global_load_dwordx4 v[70:73], v[66:67], off offset:512
	s_nop 0
	global_load_dwordx4 v[66:69], v[66:67], off offset:576
	s_nop 0
	global_load_dwordx4 v[154:157], v[174:175], off
	global_load_dwordx4 v[166:169], v[174:175], off offset:64
	global_load_dwordx4 v[170:173], v[174:175], off offset:512
	s_nop 0
	global_load_dwordx4 v[174:177], v[174:175], off offset:576
	v_or_b32_e32 v178, 16, v152
	v_ashrrev_i32_e32 v179, 31, v178
	v_lshl_add_u64 v[160:161], s[28:29], 0, v[160:161]
	v_lshlrev_b64 v[178:179], 13, v[178:179]
	v_lshl_add_u64 v[196:197], v[160:161], 0, v[178:179]
	global_load_dwordx4 v[178:181], v[196:197], off
	global_load_dwordx4 v[182:185], v[196:197], off offset:64
	global_load_dwordx4 v[186:189], v[196:197], off offset:512
	global_load_dwordx4 v[190:193], v[196:197], off offset:576
	v_lshl_add_u64 v[194:195], v[160:161], 0, v[194:195]
	s_mov_b64 s[28:29], 0x100000
	s_mov_b32 s70, s24
	s_mov_b32 s8, s26
	s_mov_b64 s[50:51], s[48:49]
	s_mov_b64 s[100:101], 0x40000
	v_lshl_add_u64 v[196:197], v[194:195], 0, s[100:101]
	global_load_dwordx4 v[224:227], v[196:197], off
	global_load_dwordx4 v[228:231], v[196:197], off offset:64
	global_load_dwordx4 v[232:235], v[196:197], off offset:512
	global_load_dwordx4 v[236:239], v[196:197], off offset:576
	s_waitcnt vmcnt(8)
	v_pk_fma_f32 v[144:145], v[144:145], v[80:81], v[156:157]
	v_pk_fma_f32 v[142:143], v[142:143], v[78:79], v[154:155]
	v_pk_fma_f32 v[140:141], v[140:141], v[76:77], v[168:169]
	v_pk_fma_f32 v[132:133], v[132:133], v[68:69], v[176:177]
	v_pk_fma_f32 v[130:131], v[130:131], v[66:67], v[174:175]
	v_pk_fma_f32 v[138:139], v[138:139], v[74:75], v[166:167]
	v_pk_fma_f32 v[136:137], v[136:137], v[72:73], v[172:173]
	v_pk_fma_f32 v[134:135], v[134:135], v[70:71], v[170:171]
	s_mov_b64 s[100:101], 0x60000
	v_lshl_add_u64 v[196:197], v[194:195], 0, s[100:101]
	global_load_dwordx4 v[154:157], v[196:197], off
	global_load_dwordx4 v[166:169], v[196:197], off offset:64
	global_load_dwordx4 v[170:173], v[196:197], off offset:512
	global_load_dwordx4 v[174:177], v[196:197], off offset:576
	global_store_dwordx4 v[194:195], v[130:133], off offset:576
	global_store_dwordx4 v[194:195], v[142:145], off
	global_store_dwordx4 v[194:195], v[138:141], off offset:64
	global_store_dwordx4 v[194:195], v[134:137], off offset:512
	s_waitcnt vmcnt(12)
	v_pk_fma_f32 v[116:117], v[116:117], v[68:69], v[192:193]
	v_pk_fma_f32 v[114:115], v[114:115], v[66:67], v[190:191]
	v_pk_fma_f32 v[128:129], v[128:129], v[80:81], v[180:181]
	v_pk_fma_f32 v[126:127], v[126:127], v[78:79], v[178:179]
	v_pk_fma_f32 v[124:125], v[124:125], v[76:77], v[184:185]
	v_pk_fma_f32 v[122:123], v[122:123], v[74:75], v[182:183]
	v_pk_fma_f32 v[120:121], v[120:121], v[72:73], v[188:189]
	v_pk_fma_f32 v[118:119], v[118:119], v[70:71], v[186:187]
	s_mov_b64 s[100:101], 0x100000
	v_lshl_add_u64 v[196:197], v[194:195], 0, s[100:101]
	global_load_dwordx4 v[178:181], v[196:197], off
	global_load_dwordx4 v[182:185], v[196:197], off offset:64
	global_load_dwordx4 v[186:189], v[196:197], off offset:512
	global_load_dwordx4 v[190:193], v[196:197], off offset:576
	s_mov_b64 s[100:101], 0x20000
	v_lshl_add_u64 v[216:217], v[194:195], 0, s[100:101]
	global_store_dwordx4 v[216:217], v[114:117], off offset:576
	global_store_dwordx4 v[216:217], v[126:129], off
	global_store_dwordx4 v[216:217], v[122:125], off offset:64
	global_store_dwordx4 v[216:217], v[118:121], off offset:512
	s_waitcnt vmcnt(16)
	v_pk_fma_f32 v[112:113], v[112:113], v[80:81], v[226:227]
	v_pk_fma_f32 v[110:111], v[110:111], v[78:79], v[224:225]
	v_pk_fma_f32 v[108:109], v[108:109], v[76:77], v[230:231]
	v_pk_fma_f32 v[106:107], v[106:107], v[74:75], v[228:229]
	v_pk_fma_f32 v[96:97], v[96:97], v[72:73], v[234:235]
	v_pk_fma_f32 v[94:95], v[94:95], v[70:71], v[232:233]
	v_pk_fma_f32 v[92:93], v[92:93], v[68:69], v[238:239]
	v_pk_fma_f32 v[90:91], v[90:91], v[66:67], v[236:237]
	s_mov_b64 s[100:101], 0x120000
	v_lshl_add_u64 v[196:197], v[194:195], 0, s[100:101]
	global_load_dwordx4 v[224:227], v[196:197], off
	global_load_dwordx4 v[228:231], v[196:197], off offset:64
	global_load_dwordx4 v[232:235], v[196:197], off offset:512
	global_load_dwordx4 v[236:239], v[196:197], off offset:576
	s_mov_b64 s[100:101], 0x40000
	v_lshl_add_u64 v[216:217], v[194:195], 0, s[100:101]
	global_store_dwordx4 v[216:217], v[110:113], off
	global_store_dwordx4 v[216:217], v[106:109], off offset:64
	global_store_dwordx4 v[216:217], v[94:97], off offset:512
	global_store_dwordx4 v[216:217], v[90:93], off offset:576
	s_waitcnt vmcnt(20)
;     __device__ __forceinline__ void operator()(const f32x4 (&acc)[2][2][4][2], const Unit& u, int wr, int wc, int fr, int fq) const {
;     ...
;         for (int gi = 0; gi < 8; ++gi) { const int ai = gi >> 2, m = gi & 3; const size_t off = (size_t)(row0 + ai * HALF + m * 16) * DM + col0;
;             if (gi + 1 < 8) { const int ai2 = (gi + 1) >> 2, m2 = (gi + 1) & 3; const size_t off2 = (size_t)(row0 + ai2 * HALF + m2 * 16) * DM + col0;
; #pragma unroll
;                 for (int bj = 0; bj < 2; ++bj)
; #pragma unroll
;                     for (int n = 0; n < 2; ++n) xn[bj][n] = *(const f32x4*)(s + off2 + bj * HALF + n * 16); }
; #pragma unroll
;             for (int bj = 0; bj < 2; ++bj)
; #pragma unroll
;                 for (int n = 0; n < 2; ++n) *(f32x4*)(d + off + bj * HALF + n * 16) = xc[bj][n] + gv[bj][n] * acc[ai][bj][m][n];
; #pragma unroll
;             for (int bj = 0; bj < 2; ++bj)
; #pragma unroll
;                 for (int n = 0; n < 2; ++n) xc[bj][n] = xn[bj][n]; }
;     }
	s_mov_b64 s[100:101], 0x60000
	v_lshl_add_u64 v[216:217], v[194:195], 0, s[100:101]
	v_pk_fma_f32 v[84:85], v[84:85], v[68:69], v[176:177]
	v_pk_fma_f32 v[82:83], v[82:83], v[66:67], v[174:175]
	global_store_dwordx4 v[216:217], v[82:85], off offset:576
	v_pk_fma_f32 v[92:93], v[104:105], v[80:81], v[156:157]
	v_pk_fma_f32 v[90:91], v[102:103], v[78:79], v[154:155]
	global_store_dwordx4 v[216:217], v[90:93], off
	v_pk_fma_f32 v[88:89], v[88:89], v[72:73], v[172:173]
	v_pk_fma_f32 v[86:87], v[86:87], v[70:71], v[170:171]
	v_pk_fma_f32 v[92:93], v[100:101], v[76:77], v[168:169]
	v_pk_fma_f32 v[90:91], v[98:99], v[74:75], v[166:167]
	s_mov_b64 s[100:101], 0x140000
	v_lshl_add_u64 v[196:197], v[194:195], 0, s[100:101]
	global_load_dwordx4 v[154:157], v[196:197], off
	global_load_dwordx4 v[166:169], v[196:197], off offset:64
	global_load_dwordx4 v[170:173], v[196:197], off offset:512
	global_load_dwordx4 v[174:177], v[196:197], off offset:576
	global_store_dwordx4 v[216:217], v[90:93], off offset:64
	global_store_dwordx4 v[216:217], v[86:89], off offset:512
	s_waitcnt vmcnt(20)
	v_pk_fma_f32 v[64:65], v[64:65], v[80:81], v[180:181]
	v_pk_fma_f32 v[62:63], v[62:63], v[78:79], v[178:179]
	v_pk_fma_f32 v[60:61], v[60:61], v[76:77], v[184:185]
	v_pk_fma_f32 v[52:53], v[52:53], v[68:69], v[192:193]
	v_pk_fma_f32 v[50:51], v[50:51], v[66:67], v[190:191]
	v_pk_fma_f32 v[58:59], v[58:59], v[74:75], v[182:183]
	v_pk_fma_f32 v[56:57], v[56:57], v[72:73], v[188:189]
	v_pk_fma_f32 v[54:55], v[54:55], v[70:71], v[186:187]
	s_mov_b64 s[100:101], 0x160000
	v_lshl_add_u64 v[196:197], v[194:195], 0, s[100:101]
	global_load_dwordx4 v[178:181], v[196:197], off
	global_load_dwordx4 v[182:185], v[196:197], off offset:64
	global_load_dwordx4 v[186:189], v[196:197], off offset:512
	global_load_dwordx4 v[190:193], v[196:197], off offset:576
	s_mov_b64 s[100:101], 0x100000
	v_lshl_add_u64 v[216:217], v[194:195], 0, s[100:101]
	global_store_dwordx4 v[216:217], v[50:53], off offset:576
	global_store_dwordx4 v[216:217], v[62:65], off
	global_store_dwordx4 v[216:217], v[58:61], off offset:64
	global_store_dwordx4 v[216:217], v[54:57], off offset:512
	s_waitcnt vmcnt(20)
	v_pk_fma_f32 v[48:49], v[48:49], v[80:81], v[226:227]
	v_pk_fma_f32 v[46:47], v[46:47], v[78:79], v[224:225]
	v_pk_fma_f32 v[44:45], v[44:45], v[76:77], v[230:231]
	v_pk_fma_f32 v[36:37], v[36:37], v[68:69], v[238:239]
	v_pk_fma_f32 v[34:35], v[34:35], v[66:67], v[236:237]
	v_pk_fma_f32 v[42:43], v[42:43], v[74:75], v[228:229]
	v_pk_fma_f32 v[40:41], v[40:41], v[72:73], v[234:235]
	v_pk_fma_f32 v[38:39], v[38:39], v[70:71], v[232:233]
	s_mov_b64 s[100:101], 0x120000
	v_lshl_add_u64 v[216:217], v[194:195], 0, s[100:101]
	global_store_dwordx4 v[216:217], v[34:37], off offset:576
	global_store_dwordx4 v[216:217], v[46:49], off
	global_store_dwordx4 v[216:217], v[42:45], off offset:64
	global_store_dwordx4 v[216:217], v[38:41], off offset:512
	s_waitcnt vmcnt(14)
	v_pk_fma_f32 v[32:33], v[32:33], v[80:81], v[156:157]
	v_pk_fma_f32 v[30:31], v[30:31], v[78:79], v[154:155]
	v_pk_fma_f32 v[28:29], v[28:29], v[76:77], v[168:169]
	v_pk_fma_f32 v[12:13], v[12:13], v[68:69], v[176:177]
	v_pk_fma_f32 v[10:11], v[10:11], v[66:67], v[174:175]
	v_pk_fma_f32 v[26:27], v[26:27], v[74:75], v[166:167]
	v_pk_fma_f32 v[20:21], v[20:21], v[72:73], v[172:173]
	v_pk_fma_f32 v[18:19], v[18:19], v[70:71], v[170:171]
	s_mov_b64 s[100:101], 0x140000
	v_lshl_add_u64 v[216:217], v[194:195], 0, s[100:101]
	global_store_dwordx4 v[216:217], v[10:13], off offset:576
	global_store_dwordx4 v[216:217], v[30:33], off
	global_store_dwordx4 v[216:217], v[26:29], off offset:64
	global_store_dwordx4 v[216:217], v[18:21], off offset:512
	s_waitcnt vmcnt(12)
	s_mov_b64 s[100:101], 0x160000
	v_lshl_add_u64 v[216:217], v[194:195], 0, s[100:101]
	v_pk_fma_f32 v[12:13], v[24:25], v[80:81], v[180:181]
	v_pk_fma_f32 v[10:11], v[22:23], v[78:79], v[178:179]
	global_store_dwordx4 v[216:217], v[10:13], off
	v_pk_fma_f32 v[8:9], v[8:9], v[72:73], v[188:189]
	v_pk_fma_f32 v[6:7], v[6:7], v[70:71], v[186:187]
	v_pk_fma_f32 v[12:13], v[16:17], v[76:77], v[184:185]
	v_pk_fma_f32 v[10:11], v[14:15], v[74:75], v[182:183]
	v_pk_fma_f32 v[4:5], v[4:5], v[68:69], v[192:193]
	v_pk_fma_f32 v[2:3], v[2:3], v[66:67], v[190:191]
	global_store_dwordx4 v[216:217], v[10:13], off offset:64
	global_store_dwordx4 v[216:217], v[6:9], off offset:512
	global_store_dwordx4 v[216:217], v[2:5], off offset:576
	s_and_b64 vcc, exec, s[40:41]
	s_mov_b64 s[28:29], s[42:43]
	s_cbranch_vccnz .LBB0_47

;     __device__ __forceinline__ void operator()(const f32x4 (&acc)[2][2][4][2], const Unit& u, int wr, int wc, int fr, int fq) const {
;         const bool lat = u.pm < 64; const int r = lat ? (u.pm >> 3) : 8;
;         const float* s = lat ? src_lat : src_ctx; float* d = lat ? dst_lat : dst_ctx;
;         const int row0 = (lat ? u.pm : u.pm - 64) * BM + wr * 64 + fr, col0 = u.pn * BM + wc * 32 + 4 * fq;
;         const float* g = gate + (size_t)r * 12288 + col0;
;         f32x4 gv[2][2];
; #pragma unroll
;         for (int bj = 0; bj < 2; ++bj)
; #pragma unroll
;             for (int n = 0; n < 2; ++n) gv[bj][n] = *(const f32x4*)(g + bj * HALF + n * 16);
;         f32x4 xc[2][2], xn[2][2];
; #pragma unroll
;         for (int bj = 0; bj < 2; ++bj)
; #pragma unroll
;             for (int n = 0; n < 2; ++n) xc[bj][n] = *(const f32x4*)(s + (size_t)row0 * DM + col0 + bj * HALF + n * 16);
; #pragma unroll
;         for (int gi = 0; gi < 8; ++gi) { const int ai = gi >> 2, m = gi & 3; const size_t off = (size_t)(row0 + ai * HALF + m * 16) * DM + col0;
;             if (gi + 1 < 8) { const int ai2 = (gi + 1) >> 2, m2 = (gi + 1) & 3; const size_t off2 = (size_t)(row0 + ai2 * HALF + m2 * 16) * DM + col0;
; #pragma unroll
;                 for (int bj = 0; bj < 2; ++bj)
; #pragma unroll
;                     for (int n = 0; n < 2; ++n) xn[bj][n] = *(const f32x4*)(s + off2 + bj * HALF + n * 16); }
; #pragma unroll
;             for (int bj = 0; bj < 2; ++bj)
; #pragma unroll
;                 for (int n = 0; n < 2; ++n) *(f32x4*)(d + off + bj * HALF + n * 16) = xc[bj][n] + gv[bj][n] * acc[ai][bj][m][n];
; #pragma unroll
;             for (int bj = 0; bj < 2; ++bj)
; #pragma unroll
;                 for (int n = 0; n < 2; ++n) xc[bj][n] = xn[bj][n]; }
;     }
.LBB0_91:
	s_lshl_b32 s8, s8, 8
	s_add_i32 s49, s8, 0xffffc000
	s_and_b64 s[38:39], s[58:59], exec
	s_cselect_b32 s8, s8, s49
	v_add_u32_e32 v162, s8, v168
	v_lshl_or_b32 v98, s76, 8, v170
	s_lshl_b64 s[38:39], s[60:61], 2
	v_ashrrev_i32_e32 v163, 31, v162
	s_add_u32 s38, s30, s38
	v_ashrrev_i32_e32 v99, 31, v98
	v_lshlrev_b64 v[164:165], 13, v[162:163]
	s_addc_u32 s39, s71, s39
	v_lshlrev_b64 v[152:153], 2, v[98:99]
	v_lshl_add_u64 v[154:155], s[56:57], 0, v[164:165]
	v_lshl_add_u64 v[98:99], s[38:39], 0, v[152:153]
	v_lshl_add_u64 v[160:161], v[154:155], 0, v[152:153]
	global_load_dwordx4 v[110:113], v[98:99], off
	global_load_dwordx4 v[106:109], v[98:99], off offset:64
	global_load_dwordx4 v[102:105], v[98:99], off offset:512
	s_nop 0
	global_load_dwordx4 v[98:101], v[98:99], off offset:576
	s_nop 0
	global_load_dwordx4 v[154:157], v[160:161], off
	global_load_dwordx4 v[172:175], v[160:161], off offset:64
	global_load_dwordx4 v[176:179], v[160:161], off offset:512
	global_load_dwordx4 v[180:183], v[160:161], off offset:576
	v_or_b32_e32 v166, 16, v162
	v_ashrrev_i32_e32 v167, 31, v166
	v_lshl_add_u64 v[160:161], s[56:57], 0, v[152:153]
	v_lshlrev_b64 v[200:201], 13, v[166:167]
	v_lshl_add_u64 v[166:167], v[160:161], 0, v[200:201]
	global_load_dwordx4 v[184:187], v[166:167], off
	global_load_dwordx4 v[188:191], v[166:167], off offset:64
	global_load_dwordx4 v[192:195], v[166:167], off offset:512
	global_load_dwordx4 v[196:199], v[166:167], off offset:576
	v_lshl_add_u64 v[152:153], s[28:29], 0, v[152:153]
	v_lshl_add_u64 v[166:167], v[152:153], 0, v[164:165]
	s_mov_b64 s[28:29], 0x100000
	s_and_b64 vcc, exec, s[40:41]
	s_mov_b32 s76, s48
	s_mov_b32 s8, s50
	s_mov_b64 s[56:57], s[54:55]
	v_lshl_add_u64 v[200:201], v[160:161], 0, v[164:165]
	s_mov_b64 s[100:101], 0x40000
	v_lshl_add_u64 v[216:217], v[200:201], 0, s[100:101]
	global_load_dwordx4 v[224:227], v[216:217], off
	global_load_dwordx4 v[228:231], v[216:217], off offset:64
	global_load_dwordx4 v[232:235], v[216:217], off offset:512
	global_load_dwordx4 v[236:239], v[216:217], off offset:576
	s_waitcnt vmcnt(8)
	v_pk_fma_f32 v[144:145], v[144:145], v[112:113], v[156:157]
	v_pk_fma_f32 v[142:143], v[142:143], v[110:111], v[154:155]
	v_pk_fma_f32 v[140:141], v[140:141], v[108:109], v[174:175]
	v_pk_fma_f32 v[132:133], v[132:133], v[100:101], v[182:183]
	v_pk_fma_f32 v[130:131], v[130:131], v[98:99], v[180:181]
	v_pk_fma_f32 v[138:139], v[138:139], v[106:107], v[172:173]
	v_pk_fma_f32 v[136:137], v[136:137], v[104:105], v[178:179]
	v_pk_fma_f32 v[134:135], v[134:135], v[102:103], v[176:177]
	s_mov_b64 s[100:101], 0x60000
	v_lshl_add_u64 v[216:217], v[200:201], 0, s[100:101]
	global_load_dwordx4 v[154:157], v[216:217], off
	global_load_dwordx4 v[172:175], v[216:217], off offset:64
	global_load_dwordx4 v[176:179], v[216:217], off offset:512
	global_load_dwordx4 v[180:183], v[216:217], off offset:576
	global_store_dwordx4 v[166:167], v[130:133], off offset:576
	global_store_dwordx4 v[166:167], v[142:145], off
	global_store_dwordx4 v[166:167], v[138:141], off offset:64
	global_store_dwordx4 v[166:167], v[134:137], off offset:512
	s_waitcnt vmcnt(12)
	v_pk_fma_f32 v[116:117], v[116:117], v[100:101], v[198:199]
	v_pk_fma_f32 v[114:115], v[114:115], v[98:99], v[196:197]
	v_pk_fma_f32 v[128:129], v[128:129], v[112:113], v[186:187]
	v_pk_fma_f32 v[126:127], v[126:127], v[110:111], v[184:185]
	v_pk_fma_f32 v[124:125], v[124:125], v[108:109], v[190:191]
	v_pk_fma_f32 v[122:123], v[122:123], v[106:107], v[188:189]
	v_pk_fma_f32 v[120:121], v[120:121], v[104:105], v[194:195]
	v_pk_fma_f32 v[118:119], v[118:119], v[102:103], v[192:193]
	s_mov_b64 s[100:101], 0x100000
	v_lshl_add_u64 v[216:217], v[200:201], 0, s[100:101]
	global_load_dwordx4 v[184:187], v[216:217], off
	global_load_dwordx4 v[188:191], v[216:217], off offset:64
	global_load_dwordx4 v[192:195], v[216:217], off offset:512
	global_load_dwordx4 v[196:199], v[216:217], off offset:576
	s_mov_b64 s[100:101], 0x20000
	v_lshl_add_u64 v[162:163], v[166:167], 0, s[100:101]
	global_store_dwordx4 v[162:163], v[114:117], off offset:576
	global_store_dwordx4 v[162:163], v[126:129], off
	global_store_dwordx4 v[162:163], v[122:125], off offset:64
	global_store_dwordx4 v[162:163], v[118:121], off offset:512
	s_waitcnt vmcnt(16)
	v_pk_fma_f32 v[96:97], v[96:97], v[112:113], v[226:227]
	v_pk_fma_f32 v[94:95], v[94:95], v[110:111], v[224:225]
	v_pk_fma_f32 v[92:93], v[92:93], v[108:109], v[230:231]
	v_pk_fma_f32 v[90:91], v[90:91], v[106:107], v[228:229]
	v_pk_fma_f32 v[80:81], v[80:81], v[104:105], v[234:235]
	v_pk_fma_f32 v[78:79], v[78:79], v[102:103], v[232:233]
	v_pk_fma_f32 v[76:77], v[76:77], v[100:101], v[238:239]
	v_pk_fma_f32 v[74:75], v[74:75], v[98:99], v[236:237]
	s_mov_b64 s[100:101], 0x120000
	v_lshl_add_u64 v[216:217], v[200:201], 0, s[100:101]
	global_load_dwordx4 v[224:227], v[216:217], off
	global_load_dwordx4 v[228:231], v[216:217], off offset:64
	global_load_dwordx4 v[232:235], v[216:217], off offset:512
	global_load_dwordx4 v[236:239], v[216:217], off offset:576
	s_mov_b64 s[100:101], 0x40000
	v_lshl_add_u64 v[162:163], v[166:167], 0, s[100:101]
	global_store_dwordx4 v[162:163], v[94:97], off
	global_store_dwordx4 v[162:163], v[90:93], off offset:64
	global_store_dwordx4 v[162:163], v[78:81], off offset:512
	global_store_dwordx4 v[162:163], v[74:77], off offset:576
	s_waitcnt vmcnt(20)
;     __device__ __forceinline__ void operator()(const f32x4 (&acc)[2][2][4][2], const Unit& u, int wr, int wc, int fr, int fq) const {
;     ...
;         for (int gi = 0; gi < 8; ++gi) { const int ai = gi >> 2, m = gi & 3; const size_t off = (size_t)(row0 + ai * HALF + m * 16) * DM + col0;
;             if (gi + 1 < 8) { const int ai2 = (gi + 1) >> 2, m2 = (gi + 1) & 3; const size_t off2 = (size_t)(row0 + ai2 * HALF + m2 * 16) * DM + col0;
; #pragma unroll
;                 for (int bj = 0; bj < 2; ++bj)
; #pragma unroll
;                     for (int n = 0; n < 2; ++n) xn[bj][n] = *(const f32x4*)(s + off2 + bj * HALF + n * 16); }
; #pragma unroll
;             for (int bj = 0; bj < 2; ++bj)
; #pragma unroll
;                 for (int n = 0; n < 2; ++n) *(f32x4*)(d + off + bj * HALF + n * 16) = xc[bj][n] + gv[bj][n] * acc[ai][bj][m][n];
; #pragma unroll
;             for (int bj = 0; bj < 2; ++bj)
; #pragma unroll
;                 for (int n = 0; n < 2; ++n) xc[bj][n] = xn[bj][n]; }
	v_pk_fma_f32 v[88:89], v[88:89], v[112:113], v[156:157]
	v_pk_fma_f32 v[72:73], v[72:73], v[104:105], v[178:179]
	v_pk_fma_f32 v[68:69], v[68:69], v[100:101], v[182:183]
	v_pk_fma_f32 v[66:67], v[66:67], v[98:99], v[180:181]
	v_pk_fma_f32 v[70:71], v[70:71], v[102:103], v[176:177]
	v_pk_fma_f32 v[86:87], v[86:87], v[110:111], v[154:155]
	v_pk_fma_f32 v[84:85], v[84:85], v[108:109], v[174:175]
	v_pk_fma_f32 v[82:83], v[82:83], v[106:107], v[172:173]
	s_mov_b64 s[100:101], 0x140000
	v_lshl_add_u64 v[216:217], v[200:201], 0, s[100:101]
	global_load_dwordx4 v[154:157], v[216:217], off
	global_load_dwordx4 v[172:175], v[216:217], off offset:64
	global_load_dwordx4 v[176:179], v[216:217], off offset:512
	global_load_dwordx4 v[180:183], v[216:217], off offset:576
	s_mov_b64 s[100:101], 0x60000
	v_lshl_add_u64 v[162:163], v[166:167], 0, s[100:101]
	global_store_dwordx4 v[162:163], v[66:69], off offset:576
	global_store_dwordx4 v[162:163], v[70:73], off offset:512
	global_store_dwordx4 v[162:163], v[86:89], off
	global_store_dwordx4 v[162:163], v[82:85], off offset:64
	s_waitcnt vmcnt(20)
	v_pk_fma_f32 v[64:65], v[64:65], v[112:113], v[186:187]
	v_pk_fma_f32 v[62:63], v[62:63], v[110:111], v[184:185]
	v_pk_fma_f32 v[60:61], v[60:61], v[108:109], v[190:191]
	v_pk_fma_f32 v[52:53], v[52:53], v[100:101], v[198:199]
	v_pk_fma_f32 v[50:51], v[50:51], v[98:99], v[196:197]
	v_pk_fma_f32 v[58:59], v[58:59], v[106:107], v[188:189]
	v_pk_fma_f32 v[56:57], v[56:57], v[104:105], v[194:195]
	v_pk_fma_f32 v[54:55], v[54:55], v[102:103], v[192:193]
	s_mov_b64 s[100:101], 0x160000
	v_lshl_add_u64 v[216:217], v[200:201], 0, s[100:101]
	global_load_dwordx4 v[184:187], v[216:217], off
	global_load_dwordx4 v[188:191], v[216:217], off offset:64
	global_load_dwordx4 v[192:195], v[216:217], off offset:512
	global_load_dwordx4 v[196:199], v[216:217], off offset:576
	s_mov_b64 s[100:101], 0x100000
	v_lshl_add_u64 v[162:163], v[166:167], 0, s[100:101]
	global_store_dwordx4 v[162:163], v[50:53], off offset:576
	global_store_dwordx4 v[162:163], v[62:65], off
	global_store_dwordx4 v[162:163], v[58:61], off offset:64
	global_store_dwordx4 v[162:163], v[54:57], off offset:512
	s_waitcnt vmcnt(20)
	v_pk_fma_f32 v[48:49], v[48:49], v[112:113], v[226:227]
	v_pk_fma_f32 v[46:47], v[46:47], v[110:111], v[224:225]
	v_pk_fma_f32 v[44:45], v[44:45], v[108:109], v[230:231]
	v_pk_fma_f32 v[36:37], v[36:37], v[100:101], v[238:239]
	v_pk_fma_f32 v[34:35], v[34:35], v[98:99], v[236:237]
	v_pk_fma_f32 v[42:43], v[42:43], v[106:107], v[228:229]
	v_pk_fma_f32 v[40:41], v[40:41], v[104:105], v[234:235]
	v_pk_fma_f32 v[38:39], v[38:39], v[102:103], v[232:233]
	s_mov_b64 s[100:101], 0x120000
	v_lshl_add_u64 v[162:163], v[166:167], 0, s[100:101]
	global_store_dwordx4 v[162:163], v[34:37], off offset:576
	global_store_dwordx4 v[162:163], v[46:49], off
	global_store_dwordx4 v[162:163], v[42:45], off offset:64
	global_store_dwordx4 v[162:163], v[38:41], off offset:512
	s_waitcnt vmcnt(16)
	v_pk_fma_f32 v[32:33], v[32:33], v[112:113], v[156:157]
	v_pk_fma_f32 v[30:31], v[30:31], v[110:111], v[154:155]
	v_pk_fma_f32 v[16:17], v[16:17], v[104:105], v[178:179]
	v_pk_fma_f32 v[14:15], v[14:15], v[102:103], v[176:177]
	v_pk_fma_f32 v[12:13], v[12:13], v[100:101], v[182:183]
	v_pk_fma_f32 v[10:11], v[10:11], v[98:99], v[180:181]
	v_pk_fma_f32 v[28:29], v[28:29], v[108:109], v[174:175]
	v_pk_fma_f32 v[26:27], v[26:27], v[106:107], v[172:173]
	s_mov_b64 s[100:101], 0x140000
	v_lshl_add_u64 v[162:163], v[166:167], 0, s[100:101]
	global_store_dwordx4 v[162:163], v[14:17], off offset:512
	global_store_dwordx4 v[162:163], v[10:13], off offset:576
	global_store_dwordx4 v[162:163], v[30:33], off
	global_store_dwordx4 v[162:163], v[26:29], off offset:64
	s_waitcnt vmcnt(12)
	s_mov_b64 s[100:101], 0x160000
	v_lshl_add_u64 v[162:163], v[166:167], 0, s[100:101]
	v_pk_fma_f32 v[12:13], v[24:25], v[112:113], v[186:187]
	v_pk_fma_f32 v[10:11], v[22:23], v[110:111], v[184:185]
	global_store_dwordx4 v[162:163], v[10:13], off
	v_pk_fma_f32 v[8:9], v[8:9], v[104:105], v[194:195]
	v_pk_fma_f32 v[6:7], v[6:7], v[102:103], v[192:193]
	v_pk_fma_f32 v[12:13], v[20:21], v[108:109], v[190:191]
	v_pk_fma_f32 v[10:11], v[18:19], v[106:107], v[188:189]
	v_pk_fma_f32 v[4:5], v[4:5], v[100:101], v[198:199]
	v_pk_fma_f32 v[2:3], v[2:3], v[98:99], v[196:197]
	global_store_dwordx4 v[162:163], v[10:13], off offset:64
	global_store_dwordx4 v[162:163], v[6:9], off offset:512
	global_store_dwordx4 v[162:163], v[2:5], off offset:576
	s_mov_b64 s[28:29], s[52:53]
	s_cbranch_vccnz .LBB0_102
